# projection epilogue stores and GU-tail weight-conversion stores write-through (sc1)
# baseline (speedup 1.0000x reference)
.LBB0_631:
	v_lshl_add_u32 v145, s47, 10, v142
	ds_read2_b32 v[146:147], v145 offset1:16
	v_lshl_or_b32 v148, s27, 8, v143
	v_lshl_add_u32 v152, s26, 8, v140
	v_ashrrev_i32_e32 v149, 31, v148
	s_andn2_b64 vcc, exec, s[34:35]
	s_waitcnt lgkmcnt(0)
	v_pk_mul_f32 v[128:129], v[128:129], v[146:147] op_sel_hi:[1,0]
	v_pk_mul_f32 v[126:127], v[126:127], v[146:147] op_sel_hi:[1,0]
	v_pk_mul_f32 v[122:123], v[122:123], v[146:147] op_sel_hi:[1,0]
	v_pk_mul_f32 v[124:125], v[124:125], v[146:147] op_sel_hi:[1,0]
	v_cvt_pk_bf16_f32 v126, v126, v127
	v_cvt_pk_bf16_f32 v127, v128, v129
	v_cvt_pk_bf16_f32 v128, v122, v123
	v_mov_b64_e32 v[122:123], s[10:11]
	v_cvt_pk_bf16_f32 v129, v124, v125
	v_mad_i64_i32 v[150:151], s[26:27], v152, s23, v[122:123]
	v_lshlrev_b64 v[124:125], 1, v[148:149]
	v_lshl_add_u64 v[148:149], v[150:151], 0, v[124:125]
	global_store_dwordx4 v[148:149], v[126:129], off sc1
	v_pk_mul_f32 v[116:117], v[116:117], v[146:147] op_sel_hi:[1,0]
	v_pk_mul_f32 v[114:115], v[114:115], v[146:147] op_sel_hi:[1,0]
	v_pk_mul_f32 v[126:127], v[108:109], v[146:147] op_sel_hi:[1,0]
	v_pk_mul_f32 v[108:109], v[106:107], v[146:147] op_sel_hi:[1,0]
	v_cvt_pk_bf16_f32 v106, v114, v115
	v_cvt_pk_bf16_f32 v107, v116, v117
	v_cvt_pk_bf16_f32 v108, v108, v109
	v_cvt_pk_bf16_f32 v109, v126, v127
	v_or_b32_e32 v115, 16, v152
	v_mov_b32_e32 v114, v147
	global_store_dwordx4 v[148:149], v[106:109], off offset:256 sc1
	v_pk_mul_f32 v[110:111], v[110:111], v[114:115] op_sel_hi:[1,0]
	v_pk_mul_f32 v[112:113], v[112:113], v[114:115] op_sel_hi:[1,0]
	v_pk_mul_f32 v[108:109], v[120:121], v[114:115] op_sel_hi:[1,0]
	v_pk_mul_f32 v[106:107], v[118:119], v[114:115] op_sel_hi:[1,0]
	v_pk_mul_f32 v[102:103], v[102:103], v[114:115] op_sel_hi:[1,0]
	v_cvt_pk_bf16_f32 v106, v106, v107
	v_cvt_pk_bf16_f32 v107, v108, v109
	v_cvt_pk_bf16_f32 v108, v110, v111
	v_mad_i64_i32 v[110:111], s[26:27], v115, s23, v[122:123]
	v_cvt_pk_bf16_f32 v109, v112, v113
	v_lshl_add_u64 v[110:111], v[110:111], 0, v[124:125]
	global_store_dwordx4 v[110:111], v[106:109], off sc1
	v_pk_mul_f32 v[104:105], v[104:105], v[114:115] op_sel_hi:[1,0]
	s_nop 0
	v_pk_mul_f32 v[106:107], v[96:97], v[114:115] op_sel_hi:[1,0]
	v_pk_mul_f32 v[96:97], v[94:95], v[114:115] op_sel_hi:[1,0]
	v_cvt_pk_bf16_f32 v94, v102, v103
	ds_read2_b32 v[102:103], v145 offset0:32 offset1:48
	v_cvt_pk_bf16_f32 v95, v104, v105
	v_cvt_pk_bf16_f32 v96, v96, v97
	v_cvt_pk_bf16_f32 v97, v106, v107
	global_store_dwordx4 v[110:111], v[94:97], off offset:256 sc1
	v_or_b32_e32 v104, 32, v152
	s_waitcnt lgkmcnt(0)
	v_pk_mul_f32 v[84:85], v[84:85], v[102:103] op_sel_hi:[1,0]
	v_pk_mul_f32 v[94:95], v[100:101], v[102:103] op_sel_hi:[1,0]
	v_pk_mul_f32 v[96:97], v[98:99], v[102:103] op_sel_hi:[1,0]
	v_pk_mul_f32 v[98:99], v[92:93], v[102:103] op_sel_hi:[1,0]
	v_pk_mul_f32 v[92:93], v[90:91], v[102:103] op_sel_hi:[1,0]
	v_cvt_pk_bf16_f32 v91, v94, v95
	v_mad_i64_i32 v[94:95], s[26:27], v104, s23, v[122:123]
	v_cvt_pk_bf16_f32 v90, v96, v97
	v_cvt_pk_bf16_f32 v92, v92, v93
	v_cvt_pk_bf16_f32 v93, v98, v99
	v_lshl_add_u64 v[94:95], v[94:95], 0, v[124:125]
	global_store_dwordx4 v[94:95], v[90:93], off sc1
	v_pk_mul_f32 v[82:83], v[82:83], v[102:103] op_sel_hi:[1,0]
	s_nop 0
	v_pk_mul_f32 v[90:91], v[76:77], v[102:103] op_sel_hi:[1,0]
	v_pk_mul_f32 v[76:77], v[74:75], v[102:103] op_sel_hi:[1,0]
	v_cvt_pk_bf16_f32 v74, v82, v83
	v_cvt_pk_bf16_f32 v75, v84, v85
	v_cvt_pk_bf16_f32 v76, v76, v77
	v_cvt_pk_bf16_f32 v77, v90, v91
	v_or_b32_e32 v83, 48, v152
	v_mov_b32_e32 v82, v103
	global_store_dwordx4 v[94:95], v[74:77], off offset:256 sc1
	v_pk_mul_f32 v[78:79], v[78:79], v[82:83] op_sel_hi:[1,0]
	v_pk_mul_f32 v[80:81], v[80:81], v[82:83] op_sel_hi:[1,0]
	v_pk_mul_f32 v[76:77], v[88:89], v[82:83] op_sel_hi:[1,0]
	v_pk_mul_f32 v[74:75], v[86:87], v[82:83] op_sel_hi:[1,0]
	v_pk_mul_f32 v[70:71], v[70:71], v[82:83] op_sel_hi:[1,0]
	v_cvt_pk_bf16_f32 v74, v74, v75
	v_cvt_pk_bf16_f32 v75, v76, v77
	v_cvt_pk_bf16_f32 v76, v78, v79
	v_mad_i64_i32 v[78:79], s[26:27], v83, s23, v[122:123]
	v_cvt_pk_bf16_f32 v77, v80, v81
	v_lshl_add_u64 v[78:79], v[78:79], 0, v[124:125]
	global_store_dwordx4 v[78:79], v[74:77], off sc1
	v_pk_mul_f32 v[72:73], v[72:73], v[82:83] op_sel_hi:[1,0]
	s_nop 0
	v_pk_mul_f32 v[74:75], v[68:69], v[82:83] op_sel_hi:[1,0]
	v_pk_mul_f32 v[68:69], v[66:67], v[82:83] op_sel_hi:[1,0]
	v_cvt_pk_bf16_f32 v66, v70, v71
	ds_read2_b32 v[70:71], v145 offset0:128 offset1:144
	v_cvt_pk_bf16_f32 v67, v72, v73
	v_cvt_pk_bf16_f32 v68, v68, v69
	v_cvt_pk_bf16_f32 v69, v74, v75
	global_store_dwordx4 v[78:79], v[66:69], off offset:256 sc1
	s_waitcnt lgkmcnt(0)
	v_pk_mul_f32 v[62:63], v[62:63], v[70:71] op_sel_hi:[1,0]
	v_pk_mul_f32 v[64:65], v[64:65], v[70:71] op_sel_hi:[1,0]
	v_add_u32_e32 v68, 0x80, v152
	v_pk_mul_f32 v[66:67], v[60:61], v[70:71] op_sel_hi:[1,0]
	v_pk_mul_f32 v[60:61], v[58:59], v[70:71] op_sel_hi:[1,0]
	v_cvt_pk_bf16_f32 v58, v62, v63
	v_mad_i64_i32 v[62:63], s[26:27], v68, s23, v[122:123]
	v_cvt_pk_bf16_f32 v59, v64, v65
	v_cvt_pk_bf16_f32 v60, v60, v61
	v_cvt_pk_bf16_f32 v61, v66, v67
	v_lshl_add_u64 v[62:63], v[62:63], 0, v[124:125]
	global_store_dwordx4 v[62:63], v[58:61], off sc1
	v_pk_mul_f32 v[52:53], v[52:53], v[70:71] op_sel_hi:[1,0]
	v_pk_mul_f32 v[50:51], v[50:51], v[70:71] op_sel_hi:[1,0]
	v_pk_mul_f32 v[58:59], v[44:45], v[70:71] op_sel_hi:[1,0]
	v_pk_mul_f32 v[44:45], v[42:43], v[70:71] op_sel_hi:[1,0]
	v_cvt_pk_bf16_f32 v42, v50, v51
	v_cvt_pk_bf16_f32 v43, v52, v53
	v_cvt_pk_bf16_f32 v44, v44, v45
	v_cvt_pk_bf16_f32 v45, v58, v59
	v_add_u32_e32 v51, 0x90, v152
	v_mov_b32_e32 v50, v71
	global_store_dwordx4 v[62:63], v[42:45], off offset:256 sc1
	v_pk_mul_f32 v[46:47], v[46:47], v[50:51] op_sel_hi:[1,0]
	v_pk_mul_f32 v[48:49], v[48:49], v[50:51] op_sel_hi:[1,0]
	v_pk_mul_f32 v[44:45], v[56:57], v[50:51] op_sel_hi:[1,0]
	v_pk_mul_f32 v[42:43], v[54:55], v[50:51] op_sel_hi:[1,0]
	v_pk_mul_f32 v[38:39], v[38:39], v[50:51] op_sel_hi:[1,0]
	v_cvt_pk_bf16_f32 v42, v42, v43
	v_cvt_pk_bf16_f32 v43, v44, v45
	v_cvt_pk_bf16_f32 v44, v46, v47
	v_mad_i64_i32 v[46:47], s[26:27], v51, s23, v[122:123]
	v_cvt_pk_bf16_f32 v45, v48, v49
	v_lshl_add_u64 v[46:47], v[46:47], 0, v[124:125]
	global_store_dwordx4 v[46:47], v[42:45], off sc1
	v_pk_mul_f32 v[40:41], v[40:41], v[50:51] op_sel_hi:[1,0]
	s_nop 0
	v_pk_mul_f32 v[42:43], v[32:33], v[50:51] op_sel_hi:[1,0]
	v_pk_mul_f32 v[32:33], v[30:31], v[50:51] op_sel_hi:[1,0]
	v_cvt_pk_bf16_f32 v30, v38, v39
	ds_read2_b32 v[38:39], v145 offset0:160 offset1:176
	v_cvt_pk_bf16_f32 v31, v40, v41
	v_cvt_pk_bf16_f32 v32, v32, v33
	v_cvt_pk_bf16_f32 v33, v42, v43
	global_store_dwordx4 v[46:47], v[30:33], off offset:256 sc1
	v_add_u32_e32 v40, 0xa0, v152
	s_waitcnt lgkmcnt(0)
	v_pk_mul_f32 v[20:21], v[20:21], v[38:39] op_sel_hi:[1,0]
	v_pk_mul_f32 v[30:31], v[36:37], v[38:39] op_sel_hi:[1,0]
	v_pk_mul_f32 v[32:33], v[34:35], v[38:39] op_sel_hi:[1,0]
	v_pk_mul_f32 v[34:35], v[28:29], v[38:39] op_sel_hi:[1,0]
	v_pk_mul_f32 v[28:29], v[26:27], v[38:39] op_sel_hi:[1,0]
	v_cvt_pk_bf16_f32 v27, v30, v31
	v_mad_i64_i32 v[30:31], s[26:27], v40, s23, v[122:123]
	v_cvt_pk_bf16_f32 v26, v32, v33
	v_cvt_pk_bf16_f32 v28, v28, v29
	v_cvt_pk_bf16_f32 v29, v34, v35
	v_lshl_add_u64 v[30:31], v[30:31], 0, v[124:125]
	global_store_dwordx4 v[30:31], v[26:29], off sc1
	v_pk_mul_f32 v[18:19], v[18:19], v[38:39] op_sel_hi:[1,0]
	s_nop 0
	v_pk_mul_f32 v[26:27], v[12:13], v[38:39] op_sel_hi:[1,0]
	v_pk_mul_f32 v[12:13], v[10:11], v[38:39] op_sel_hi:[1,0]
	v_cvt_pk_bf16_f32 v10, v18, v19
	v_cvt_pk_bf16_f32 v11, v20, v21
	v_cvt_pk_bf16_f32 v12, v12, v13
	v_cvt_pk_bf16_f32 v13, v26, v27
	v_add_u32_e32 v19, 0xb0, v152
	v_mov_b32_e32 v18, v39
	global_store_dwordx4 v[30:31], v[10:13], off offset:256 sc1
	v_pk_mul_f32 v[14:15], v[14:15], v[18:19] op_sel_hi:[1,0]
	v_pk_mul_f32 v[16:17], v[16:17], v[18:19] op_sel_hi:[1,0]
	v_pk_mul_f32 v[12:13], v[24:25], v[18:19] op_sel_hi:[1,0]
	v_pk_mul_f32 v[10:11], v[22:23], v[18:19] op_sel_hi:[1,0]
	v_pk_mul_f32 v[8:9], v[8:9], v[18:19] op_sel_hi:[1,0]
	v_cvt_pk_bf16_f32 v10, v10, v11
	v_cvt_pk_bf16_f32 v11, v12, v13
	v_cvt_pk_bf16_f32 v12, v14, v15
	v_mad_i64_i32 v[14:15], s[26:27], v19, s23, v[122:123]
	v_cvt_pk_bf16_f32 v13, v16, v17
	v_lshl_add_u64 v[14:15], v[14:15], 0, v[124:125]
	global_store_dwordx4 v[14:15], v[10:13], off sc1
	v_pk_mul_f32 v[6:7], v[6:7], v[18:19] op_sel_hi:[1,0]
	s_mov_b64 s[26:27], -1
	v_pk_mul_f32 v[10:11], v[4:5], v[18:19] op_sel_hi:[1,0]
	v_pk_mul_f32 v[4:5], v[2:3], v[18:19] op_sel_hi:[1,0]
	v_cvt_pk_bf16_f32 v2, v6, v7
	v_cvt_pk_bf16_f32 v3, v8, v9
	v_cvt_pk_bf16_f32 v4, v4, v5
	v_cvt_pk_bf16_f32 v5, v10, v11
	global_store_dwordx4 v[14:15], v[2:5], off offset:256 sc1
	s_cbranch_vccnz .LBB0_624
	s_andn2_b64 vcc, exec, s[2:3]
	s_cbranch_vccnz .LBB0_623
	s_barrier
	s_branch .LBB0_623

.LBB0_863:
	s_waitcnt vmcnt(0)
	v_pk_mul_f32 v[2:3], v[2:3], v[0:1] op_sel_hi:[1,0]
	v_add_u32_e32 v6, 0x2cb0, v98
	ds_write2_b32 v6, v2, v3 offset1:1
	v_pk_mul_f32 v[2:3], v[4:5], v[0:1] op_sel_hi:[1,0]
	v_add_u32_e32 v0, 0x2cb8, v98
	ds_write2_b32 v0, v2, v3 offset1:1
	s_waitcnt lgkmcnt(0)
	v_add_u32_e32 v0, 0x400, v87
	ds_read2_b32 v[8:9], v87 offset0:65 offset1:73
	ds_read2_b32 v[10:11], v87 offset1:8
	ds_read2_b32 v[12:13], v87 offset0:130 offset1:138
	ds_read2_b32 v[14:15], v87 offset0:195 offset1:203
	ds_read2_b32 v[16:17], v0 offset0:4 offset1:12
	ds_read2_b32 v[18:19], v0 offset0:69 offset1:77
	ds_read2_b32 v[20:21], v0 offset0:134 offset1:142
	ds_read2_b32 v[22:23], v0 offset0:199 offset1:207
	v_add_u32_e32 v24, s10, v86
	v_ashrrev_i32_e32 v25, 31, v24
	v_lshl_add_u64 v[2:3], s[12:13], 1, v[76:77]
	v_lshlrev_b64 v[26:27], 11, v[24:25]
	s_waitcnt lgkmcnt(6)
	v_cvt_pk_bf16_f32 v4, v10, v8
	s_waitcnt lgkmcnt(4)
	v_cvt_pk_bf16_f32 v5, v12, v14
	s_waitcnt lgkmcnt(2)
	v_cvt_pk_bf16_f32 v6, v16, v18
	s_waitcnt lgkmcnt(0)
	v_cvt_pk_bf16_f32 v7, v20, v22
	v_lshl_add_u64 v[26:27], v[2:3], 0, v[26:27]
	v_add_u32_e32 v8, 8, v24
	global_store_dwordx4 v[26:27], v[4:7], off sc1
	v_add_u32_e32 v26, 16, v24
	v_ashrrev_i32_e32 v27, 31, v26
	v_cvt_pk_bf16_f32 v4, v11, v9
	v_ashrrev_i32_e32 v9, 31, v8
	v_lshlrev_b64 v[8:9], 11, v[8:9]
	v_cvt_pk_bf16_f32 v5, v13, v15
	v_cvt_pk_bf16_f32 v6, v17, v19
	v_cvt_pk_bf16_f32 v7, v21, v23
	v_lshl_add_u64 v[8:9], v[2:3], 0, v[8:9]
	global_store_dwordx4 v[8:9], v[4:7], off sc1
	ds_read2_b32 v[8:9], v87 offset0:81 offset1:89
	ds_read2_b32 v[10:11], v87 offset0:16 offset1:24
	ds_read2_b32 v[12:13], v87 offset0:146 offset1:154
	ds_read2_b32 v[14:15], v87 offset0:211 offset1:219
	ds_read2_b32 v[16:17], v0 offset0:20 offset1:28
	ds_read2_b32 v[18:19], v0 offset0:85 offset1:93
	ds_read2_b32 v[20:21], v0 offset0:150 offset1:158
	ds_read2_b32 v[22:23], v0 offset0:215 offset1:223
	v_lshlrev_b64 v[26:27], 11, v[26:27]
	s_waitcnt lgkmcnt(6)
	v_cvt_pk_bf16_f32 v4, v10, v8
	s_waitcnt lgkmcnt(4)
	v_cvt_pk_bf16_f32 v5, v12, v14
	s_waitcnt lgkmcnt(2)
	v_cvt_pk_bf16_f32 v6, v16, v18
	s_waitcnt lgkmcnt(0)
	v_cvt_pk_bf16_f32 v7, v20, v22
	v_lshl_add_u64 v[26:27], v[2:3], 0, v[26:27]
	v_add_u32_e32 v8, 24, v24
	global_store_dwordx4 v[26:27], v[4:7], off sc1
	v_add_u32_e32 v26, 32, v24
	v_ashrrev_i32_e32 v27, 31, v26
	v_cvt_pk_bf16_f32 v4, v11, v9
	v_ashrrev_i32_e32 v9, 31, v8
	v_lshlrev_b64 v[8:9], 11, v[8:9]
	v_cvt_pk_bf16_f32 v5, v13, v15
	v_cvt_pk_bf16_f32 v6, v17, v19
	v_cvt_pk_bf16_f32 v7, v21, v23
	v_lshl_add_u64 v[8:9], v[2:3], 0, v[8:9]
	global_store_dwordx4 v[8:9], v[4:7], off sc1
	ds_read2_b32 v[8:9], v87 offset0:32 offset1:40
	ds_read2_b32 v[10:11], v87 offset0:97 offset1:105
	ds_read2_b32 v[12:13], v87 offset0:162 offset1:170
	ds_read2_b32 v[14:15], v87 offset0:227 offset1:235
	ds_read2_b32 v[16:17], v0 offset0:36 offset1:44
	ds_read2_b32 v[18:19], v0 offset0:101 offset1:109
	ds_read2_b32 v[20:21], v0 offset0:166 offset1:174
	ds_read2_b32 v[22:23], v0 offset0:231 offset1:239
	v_lshlrev_b64 v[26:27], 11, v[26:27]
	s_waitcnt lgkmcnt(6)
	v_cvt_pk_bf16_f32 v4, v8, v10
	s_waitcnt lgkmcnt(4)
	v_cvt_pk_bf16_f32 v5, v12, v14
	s_waitcnt lgkmcnt(2)
	v_cvt_pk_bf16_f32 v6, v16, v18
	s_waitcnt lgkmcnt(0)
	v_cvt_pk_bf16_f32 v7, v20, v22
	v_lshl_add_u64 v[26:27], v[2:3], 0, v[26:27]
	v_add_u32_e32 v8, 40, v24
	global_store_dwordx4 v[26:27], v[4:7], off sc1
	v_add_u32_e32 v26, 48, v24
	v_ashrrev_i32_e32 v27, 31, v26
	v_cvt_pk_bf16_f32 v4, v9, v11
	v_ashrrev_i32_e32 v9, 31, v8
	v_lshlrev_b64 v[8:9], 11, v[8:9]
	v_cvt_pk_bf16_f32 v5, v13, v15
	v_cvt_pk_bf16_f32 v6, v17, v19
	v_cvt_pk_bf16_f32 v7, v21, v23
	v_lshl_add_u64 v[8:9], v[2:3], 0, v[8:9]
	global_store_dwordx4 v[8:9], v[4:7], off sc1
	ds_read2_b32 v[8:9], v87 offset0:48 offset1:56
	ds_read2_b32 v[10:11], v87 offset0:113 offset1:121
	ds_read2_b32 v[12:13], v87 offset0:178 offset1:186
	ds_read2_b32 v[14:15], v87 offset0:243 offset1:251
	ds_read2_b32 v[16:17], v0 offset0:52 offset1:60
	ds_read2_b32 v[18:19], v0 offset0:117 offset1:125
	ds_read2_b32 v[20:21], v0 offset0:182 offset1:190
	ds_read2_b32 v[22:23], v0 offset0:247 offset1:255
	v_lshlrev_b64 v[26:27], 11, v[26:27]
	s_waitcnt lgkmcnt(6)
	v_cvt_pk_bf16_f32 v4, v8, v10
	s_waitcnt lgkmcnt(4)
	v_cvt_pk_bf16_f32 v5, v12, v14
	s_waitcnt lgkmcnt(2)
	v_cvt_pk_bf16_f32 v6, v16, v18
	s_waitcnt lgkmcnt(0)
	v_cvt_pk_bf16_f32 v7, v20, v22
	v_lshl_add_u64 v[26:27], v[2:3], 0, v[26:27]
	v_add_u32_e32 v8, 56, v24
	global_store_dwordx4 v[26:27], v[4:7], off sc1
	s_nop 1
	v_cvt_pk_bf16_f32 v4, v9, v11
	v_ashrrev_i32_e32 v9, 31, v8
	v_lshlrev_b64 v[8:9], 11, v[8:9]
	v_cvt_pk_bf16_f32 v5, v13, v15
	v_cvt_pk_bf16_f32 v6, v17, v19
	v_cvt_pk_bf16_f32 v7, v21, v23
	v_lshl_add_u64 v[2:3], v[2:3], 0, v[8:9]
	global_store_dwordx4 v[2:3], v[4:7], off sc1
	s_waitcnt lgkmcnt(0)

.LBB0_865:
	s_cmpk_gt_i32 s18, 0x2ff
	s_mov_b64 s[10:11], -1
	s_cbranch_scc0 .LBB0_875
	s_cmpk_gt_u32 s18, 0x3ff
	s_cbranch_scc0 .LBB0_872
	s_cmpk_gt_u32 s18, 0x43f
	v_lshlrev_b32_e32 v0, 2, v68
	s_cbranch_scc0 .LBB0_869
	s_add_i32 s0, s18, 0xfffffbc0
	s_lshr_b32 s0, s0, 6
	v_readlane_b32 s36, v253, 1
	s_lshl_b64 s[10:11], s[0:1], 20
	v_readlane_b32 s42, v253, 7
	v_readlane_b32 s43, v253, 8
	s_add_u32 s12, s42, s10
	s_addc_u32 s13, s43, s11
	s_and_b32 s14, s7, 64
	s_lshl_b32 s0, s0, 7
	s_and_b32 s11, s9, 0x7c0
	s_or_b32 s10, s0, s14
	s_lshl_b32 s0, s14, 2
	s_add_u32 s12, s12, s0
	v_or_b32_e32 v4, s11, v66
	s_addc_u32 s13, s13, 0
	v_lshl_add_u64 v[2:3], s[12:13], 0, v[0:1]
	v_lshlrev_b32_e32 v4, 9, v4
	v_mov_b32_e32 v5, v1
	v_lshl_add_u64 v[58:59], v[2:3], 0, v[4:5]
	global_load_dwordx4 v[2:5], v[58:59], off
	global_load_dwordx4 v[6:9], v[58:59], off offset:2048
	s_movk_i32 s0, 0x1000
	v_add_co_u32_e32 v14, vcc, s0, v58
	s_movk_i32 s0, 0x2000
	s_nop 0
	v_addc_co_u32_e32 v15, vcc, 0, v59, vcc
	v_add_co_u32_e32 v22, vcc, s0, v58
	s_movk_i32 s0, 0x3000
	s_nop 0
	v_addc_co_u32_e32 v23, vcc, 0, v59, vcc
	global_load_dwordx4 v[10:13], v[22:23], off offset:-4096
	s_nop 0
	global_load_dwordx4 v[14:17], v[14:15], off offset:2048
	s_nop 0
	global_load_dwordx4 v[18:21], v[22:23], off
	s_nop 0
	global_load_dwordx4 v[22:25], v[22:23], off offset:2048
	v_add_co_u32_e32 v30, vcc, s0, v58
	s_movk_i32 s0, 0x4000
	s_nop 0
	v_addc_co_u32_e32 v31, vcc, 0, v59, vcc
	v_add_co_u32_e32 v38, vcc, s0, v58
	s_movk_i32 s0, 0x5000
	s_nop 0
	v_addc_co_u32_e32 v39, vcc, 0, v59, vcc
	global_load_dwordx4 v[26:29], v[38:39], off offset:-4096
	s_nop 0
	global_load_dwordx4 v[30:33], v[30:31], off offset:2048
	s_nop 0
	global_load_dwordx4 v[34:37], v[38:39], off
	s_nop 0
	global_load_dwordx4 v[38:41], v[38:39], off offset:2048
	v_add_co_u32_e32 v46, vcc, s0, v58
	s_movk_i32 s0, 0x6000
	s_nop 0
	v_addc_co_u32_e32 v47, vcc, 0, v59, vcc
	v_add_co_u32_e32 v54, vcc, s0, v58
	s_movk_i32 s0, 0x7000
	s_nop 0
	v_addc_co_u32_e32 v55, vcc, 0, v59, vcc
	global_load_dwordx4 v[42:45], v[54:55], off offset:-4096
	s_nop 0
	global_load_dwordx4 v[46:49], v[46:47], off offset:2048
	s_nop 0
	global_load_dwordx4 v[50:53], v[54:55], off
	s_nop 0
	global_load_dwordx4 v[54:57], v[54:55], off offset:2048
	v_add_co_u32_e32 v62, vcc, s0, v58
	s_lshl_b32 s0, s11, 1
	s_nop 0
	v_addc_co_u32_e32 v63, vcc, 0, v59, vcc
	global_load_dwordx4 v[58:61], v[62:63], off
	s_nop 0
	global_load_dwordx4 v[62:65], v[62:63], off offset:2048
	v_readlane_b32 s37, v253, 2
	v_readlane_b32 s38, v253, 3
	v_readlane_b32 s39, v253, 4
	v_readlane_b32 s40, v253, 5
	v_readlane_b32 s41, v253, 6
	v_readlane_b32 s44, v253, 9
	v_readlane_b32 s45, v253, 10
	v_readlane_b32 s46, v253, 11
	v_readlane_b32 s47, v253, 12
	v_readlane_b32 s48, v253, 13
	v_readlane_b32 s49, v253, 14
	v_readlane_b32 s50, v253, 15
	v_readlane_b32 s51, v253, 16
	s_waitcnt vmcnt(0)
	ds_write2_b32 v69, v2, v3 offset1:1
	ds_write2_b32 v69, v4, v5 offset0:2 offset1:3
	v_add_u32_e32 v2, 0x410, v69
	ds_write2_b32 v2, v6, v7 offset1:1
	v_add_u32_e32 v2, 0x418, v69
	ds_write2_b32 v2, v8, v9 offset1:1
	v_add_u32_e32 v2, 0x820, v69
	ds_write2_b32 v2, v10, v11 offset1:1
	v_add_u32_e32 v2, 0x828, v69
	ds_write2_b32 v2, v12, v13 offset1:1
	v_add_u32_e32 v2, 0xc30, v69
	ds_write2_b32 v2, v14, v15 offset1:1
	v_add_u32_e32 v2, 0xc38, v69
	ds_write2_b32 v2, v16, v17 offset1:1
	v_add_u32_e32 v2, 0x1040, v69
	ds_write2_b32 v2, v18, v19 offset1:1
	v_add_u32_e32 v2, 0x1048, v69
	ds_write2_b32 v2, v20, v21 offset1:1
	v_add_u32_e32 v2, 0x1450, v69
	ds_write2_b32 v2, v22, v23 offset1:1
	v_add_u32_e32 v2, 0x1458, v69
	ds_write2_b32 v2, v24, v25 offset1:1
	v_add_u32_e32 v2, 0x1860, v69
	ds_write2_b32 v2, v26, v27 offset1:1
	v_add_u32_e32 v2, 0x1868, v69
	ds_write2_b32 v2, v28, v29 offset1:1
	v_add_u32_e32 v2, 0x1c70, v69
	ds_write2_b32 v2, v30, v31 offset1:1
	v_add_u32_e32 v2, 0x1c78, v69
	ds_write2_b32 v2, v32, v33 offset1:1
	v_add_u32_e32 v2, 0x2080, v69
	ds_write2_b32 v2, v34, v35 offset1:1
	v_add_u32_e32 v2, 0x2088, v69
	ds_write2_b32 v2, v36, v37 offset1:1
	v_add_u32_e32 v2, 0x2490, v69
	ds_write2_b32 v2, v38, v39 offset1:1
	v_add_u32_e32 v2, 0x2498, v69
	ds_write2_b32 v2, v40, v41 offset1:1
	v_add_u32_e32 v2, 0x28a0, v69
	ds_write2_b32 v2, v42, v43 offset1:1
	v_add_u32_e32 v2, 0x28a8, v69
	ds_write2_b32 v2, v44, v45 offset1:1
	v_add_u32_e32 v2, 0x2cb0, v69
	ds_write2_b32 v2, v46, v47 offset1:1
	v_add_u32_e32 v2, 0x2cb8, v69
	ds_write2_b32 v2, v48, v49 offset1:1
	v_add_u32_e32 v2, 0x30c0, v69
	ds_write2_b32 v2, v50, v51 offset1:1
	v_add_u32_e32 v2, 0x30c8, v69
	ds_write2_b32 v2, v52, v53 offset1:1
	v_add_u32_e32 v2, 0x34d0, v69
	ds_write2_b32 v2, v54, v55 offset1:1
	v_add_u32_e32 v2, 0x34d8, v69
	ds_write2_b32 v2, v56, v57 offset1:1
	v_add_u32_e32 v2, 0x38e0, v69
	ds_write2_b32 v2, v58, v59 offset1:1
	v_add_u32_e32 v2, 0x38e8, v69
	ds_write2_b32 v2, v60, v61 offset1:1
	v_add_u32_e32 v2, 0x3cf0, v69
	ds_write2_b32 v2, v62, v63 offset1:1
	v_add_u32_e32 v2, 0x3cf8, v69
	ds_write2_b32 v2, v64, v65 offset1:1
	s_waitcnt lgkmcnt(0)
	v_add_u32_e32 v26, 0x400, v87
	ds_read2_b32 v[8:9], v87 offset0:65 offset1:73
	ds_read2_b32 v[10:11], v87 offset1:8
	ds_read2_b32 v[12:13], v87 offset0:130 offset1:138
	ds_read2_b32 v[14:15], v87 offset0:195 offset1:203
	ds_read2_b32 v[16:17], v26 offset0:4 offset1:12
	ds_read2_b32 v[18:19], v26 offset0:69 offset1:77
	ds_read2_b32 v[20:21], v26 offset0:134 offset1:142
	ds_read2_b32 v[22:23], v26 offset0:199 offset1:207
	v_or_b32_e32 v24, s10, v86
	v_mov_b32_e32 v25, v1
	v_lshl_add_u64 v[2:3], v[70:71], 0, s[0:1]
	v_lshlrev_b64 v[24:25], 12, v[24:25]
	s_waitcnt lgkmcnt(6)
	v_cvt_pk_bf16_f32 v4, v10, v8
	s_waitcnt lgkmcnt(4)
	v_cvt_pk_bf16_f32 v5, v12, v14
	s_waitcnt lgkmcnt(2)
	v_cvt_pk_bf16_f32 v6, v16, v18
	s_waitcnt lgkmcnt(0)
	v_cvt_pk_bf16_f32 v7, v20, v22
	v_lshl_add_u64 v[24:25], v[2:3], 0, v[24:25]
	global_store_dwordx4 v[24:25], v[4:7], off sc1
	v_or_b32_e32 v8, s10, v88
	v_or_b32_e32 v24, s10, v89
	v_cvt_pk_bf16_f32 v4, v11, v9
	v_mov_b32_e32 v9, v1
	v_lshlrev_b64 v[8:9], 12, v[8:9]
	v_cvt_pk_bf16_f32 v5, v13, v15
	v_cvt_pk_bf16_f32 v6, v17, v19
	v_cvt_pk_bf16_f32 v7, v21, v23
	v_lshl_add_u64 v[8:9], v[2:3], 0, v[8:9]
	global_store_dwordx4 v[8:9], v[4:7], off sc1
	ds_read2_b32 v[8:9], v87 offset0:81 offset1:89
	ds_read2_b32 v[10:11], v87 offset0:16 offset1:24
	ds_read2_b32 v[12:13], v87 offset0:146 offset1:154
	ds_read2_b32 v[14:15], v87 offset0:211 offset1:219
	ds_read2_b32 v[16:17], v26 offset0:20 offset1:28
	ds_read2_b32 v[18:19], v26 offset0:85 offset1:93
	ds_read2_b32 v[20:21], v26 offset0:150 offset1:158
	ds_read2_b32 v[22:23], v26 offset0:215 offset1:223
	v_mov_b32_e32 v25, v1
	v_lshlrev_b64 v[24:25], 12, v[24:25]
	s_waitcnt lgkmcnt(6)
	v_cvt_pk_bf16_f32 v4, v10, v8
	s_waitcnt lgkmcnt(4)
	v_cvt_pk_bf16_f32 v5, v12, v14
	s_waitcnt lgkmcnt(2)
	v_cvt_pk_bf16_f32 v6, v16, v18
	s_waitcnt lgkmcnt(0)
	v_cvt_pk_bf16_f32 v7, v20, v22
	v_lshl_add_u64 v[24:25], v[2:3], 0, v[24:25]
	global_store_dwordx4 v[24:25], v[4:7], off sc1
	v_or_b32_e32 v8, s10, v90
	v_or_b32_e32 v24, s10, v91
	v_cvt_pk_bf16_f32 v4, v11, v9
	v_mov_b32_e32 v9, v1
	v_lshlrev_b64 v[8:9], 12, v[8:9]
	v_cvt_pk_bf16_f32 v5, v13, v15
	v_cvt_pk_bf16_f32 v6, v17, v19
	v_cvt_pk_bf16_f32 v7, v21, v23
	v_lshl_add_u64 v[8:9], v[2:3], 0, v[8:9]
	global_store_dwordx4 v[8:9], v[4:7], off sc1
	ds_read2_b32 v[8:9], v87 offset0:32 offset1:40
	ds_read2_b32 v[10:11], v87 offset0:97 offset1:105
	ds_read2_b32 v[12:13], v87 offset0:162 offset1:170
	ds_read2_b32 v[14:15], v87 offset0:227 offset1:235
	ds_read2_b32 v[16:17], v26 offset0:36 offset1:44
	ds_read2_b32 v[18:19], v26 offset0:101 offset1:109
	ds_read2_b32 v[20:21], v26 offset0:166 offset1:174
	ds_read2_b32 v[22:23], v26 offset0:231 offset1:239
	v_mov_b32_e32 v25, v1
	v_lshlrev_b64 v[24:25], 12, v[24:25]
	s_waitcnt lgkmcnt(6)
	v_cvt_pk_bf16_f32 v4, v8, v10
	s_waitcnt lgkmcnt(4)
	v_cvt_pk_bf16_f32 v5, v12, v14
	s_waitcnt lgkmcnt(2)
	v_cvt_pk_bf16_f32 v6, v16, v18
	s_waitcnt lgkmcnt(0)
	v_cvt_pk_bf16_f32 v7, v20, v22
	v_lshl_add_u64 v[24:25], v[2:3], 0, v[24:25]
	global_store_dwordx4 v[24:25], v[4:7], off sc1
	v_or_b32_e32 v8, s10, v92
	v_or_b32_e32 v24, s10, v93
	v_cvt_pk_bf16_f32 v4, v9, v11
	v_mov_b32_e32 v9, v1
	v_lshlrev_b64 v[8:9], 12, v[8:9]
	v_cvt_pk_bf16_f32 v5, v13, v15
	v_cvt_pk_bf16_f32 v6, v17, v19
	v_cvt_pk_bf16_f32 v7, v21, v23
	v_lshl_add_u64 v[8:9], v[2:3], 0, v[8:9]
	global_store_dwordx4 v[8:9], v[4:7], off sc1
	ds_read2_b32 v[8:9], v87 offset0:48 offset1:56
	ds_read2_b32 v[10:11], v87 offset0:113 offset1:121
	ds_read2_b32 v[12:13], v87 offset0:178 offset1:186
	ds_read2_b32 v[14:15], v87 offset0:243 offset1:251
	ds_read2_b32 v[16:17], v26 offset0:52 offset1:60
	ds_read2_b32 v[18:19], v26 offset0:117 offset1:125
	ds_read2_b32 v[20:21], v26 offset0:182 offset1:190
	ds_read2_b32 v[22:23], v26 offset0:247 offset1:255
	v_mov_b32_e32 v25, v1
	v_lshlrev_b64 v[24:25], 12, v[24:25]
	s_waitcnt lgkmcnt(6)
	v_cvt_pk_bf16_f32 v4, v8, v10
	s_waitcnt lgkmcnt(4)
	v_cvt_pk_bf16_f32 v5, v12, v14
	s_waitcnt lgkmcnt(2)
	v_cvt_pk_bf16_f32 v6, v16, v18
	s_waitcnt lgkmcnt(0)
	v_cvt_pk_bf16_f32 v7, v20, v22
	v_lshl_add_u64 v[24:25], v[2:3], 0, v[24:25]
	global_store_dwordx4 v[24:25], v[4:7], off sc1
	v_or_b32_e32 v8, s10, v94
	s_mov_b64 s[10:11], 0
	v_cvt_pk_bf16_f32 v4, v9, v11
	v_mov_b32_e32 v9, v1
	v_lshlrev_b64 v[8:9], 12, v[8:9]
	v_cvt_pk_bf16_f32 v5, v13, v15
	v_cvt_pk_bf16_f32 v6, v17, v19
	v_cvt_pk_bf16_f32 v7, v21, v23
	v_lshl_add_u64 v[2:3], v[2:3], 0, v[8:9]
	global_store_dwordx4 v[2:3], v[4:7], off sc1
	s_waitcnt lgkmcnt(0)
.LBB0_869:
	s_andn2_b64 vcc, exec, s[10:11]
	s_cbranch_vccnz .LBB0_871
	s_add_i32 s0, s18, 0xfffffc00
	s_lshr_b32 s0, s0, 4
	v_readlane_b32 s36, v253, 1
	s_lshl_b64 s[10:11], s[0:1], 18
	v_readlane_b32 s50, v253, 15
	v_readlane_b32 s51, v253, 16
	s_add_u32 s12, s50, s10
	s_addc_u32 s13, s51, s11
	s_and_b32 s14, s7, 0xc0
	s_lshl_b32 s0, s0, 8
	s_and_b32 s11, s16, 0xc0
	s_or_b32 s10, s0, s14
	s_lshl_b32 s0, s14, 2
	s_add_u32 s12, s12, s0
	v_or_b32_e32 v4, s11, v66
	s_addc_u32 s13, s13, 0
	v_lshl_add_u64 v[2:3], s[12:13], 0, v[0:1]
	v_lshlrev_b32_e32 v0, 10, v4
	v_lshl_add_u64 v[62:63], v[2:3], 0, v[0:1]
	s_movk_i32 s0, 0x2000
	v_add_co_u32_e32 v10, vcc, s0, v62
	global_load_dwordx4 v[2:5], v[62:63], off
	s_nop 0
	v_addc_co_u32_e32 v11, vcc, 0, v63, vcc
	global_load_dwordx4 v[6:9], v[10:11], off offset:-4096
	s_nop 0
	global_load_dwordx4 v[10:13], v[10:11], off
	s_movk_i32 s0, 0x4000
	v_add_co_u32_e32 v18, vcc, s0, v62
	s_movk_i32 s0, 0x6000
	s_nop 0
	v_addc_co_u32_e32 v19, vcc, 0, v63, vcc
	global_load_dwordx4 v[14:17], v[18:19], off offset:-4096
	s_nop 0
	global_load_dwordx4 v[18:21], v[18:19], off
	v_add_co_u32_e32 v26, vcc, s0, v62
	s_mov_b32 s0, 0x8000
	s_nop 0
	v_addc_co_u32_e32 v27, vcc, 0, v63, vcc
	global_load_dwordx4 v[22:25], v[26:27], off offset:-4096
	s_nop 0
	global_load_dwordx4 v[26:29], v[26:27], off
	v_add_co_u32_e32 v34, vcc, s0, v62
	s_mov_b32 s0, 0xa000
	s_nop 0
	v_addc_co_u32_e32 v35, vcc, 0, v63, vcc
	global_load_dwordx4 v[30:33], v[34:35], off offset:-4096
	s_nop 0
	global_load_dwordx4 v[34:37], v[34:35], off
	v_add_co_u32_e32 v42, vcc, s0, v62
	s_mov_b32 s0, 0xc000
	s_nop 0
	v_addc_co_u32_e32 v43, vcc, 0, v63, vcc
	global_load_dwordx4 v[38:41], v[42:43], off offset:-4096
	s_nop 0
	global_load_dwordx4 v[42:45], v[42:43], off
	v_add_co_u32_e32 v50, vcc, s0, v62
	s_mov_b32 s0, 0xe000
	s_nop 0
	v_addc_co_u32_e32 v51, vcc, 0, v63, vcc
	global_load_dwordx4 v[46:49], v[50:51], off offset:-4096
	s_nop 0
	global_load_dwordx4 v[50:53], v[50:51], off
	v_add_co_u32_e32 v58, vcc, s0, v62
	s_mov_b32 s0, 0xf000
	s_nop 0
	v_addc_co_u32_e32 v59, vcc, 0, v63, vcc
	global_load_dwordx4 v[54:57], v[58:59], off offset:-4096
	s_nop 0
	global_load_dwordx4 v[58:61], v[58:59], off
	v_add_co_u32_e32 v62, vcc, s0, v62
	v_add_u32_e32 v0, 0x410, v69
	s_nop 0
	v_addc_co_u32_e32 v63, vcc, 0, v63, vcc
	global_load_dwordx4 v[62:65], v[62:63], off
	s_lshl_b32 s0, s11, 1
	v_readlane_b32 s37, v253, 2
	v_readlane_b32 s38, v253, 3
	v_readlane_b32 s39, v253, 4
	v_readlane_b32 s40, v253, 5
	v_readlane_b32 s41, v253, 6
	v_readlane_b32 s42, v253, 7
	v_readlane_b32 s43, v253, 8
	v_readlane_b32 s44, v253, 9
	v_readlane_b32 s45, v253, 10
	v_readlane_b32 s46, v253, 11
	v_readlane_b32 s47, v253, 12
	v_readlane_b32 s48, v253, 13
	v_readlane_b32 s49, v253, 14
	s_waitcnt vmcnt(0)
	ds_write2_b32 v69, v2, v3 offset1:1
	ds_write2_b32 v69, v4, v5 offset0:2 offset1:3
	v_lshl_add_u64 v[2:3], v[72:73], 0, s[0:1]
	ds_write2_b32 v0, v6, v7 offset1:1
	v_add_u32_e32 v0, 0x418, v69
	ds_write2_b32 v0, v8, v9 offset1:1
	v_add_u32_e32 v0, 0x820, v69
	ds_write2_b32 v0, v10, v11 offset1:1
	v_add_u32_e32 v0, 0x828, v69
	ds_write2_b32 v0, v12, v13 offset1:1
	v_add_u32_e32 v0, 0xc30, v69
	ds_write2_b32 v0, v14, v15 offset1:1
	v_add_u32_e32 v0, 0xc38, v69
	ds_write2_b32 v0, v16, v17 offset1:1
	v_add_u32_e32 v0, 0x1040, v69
	ds_write2_b32 v0, v18, v19 offset1:1
	v_add_u32_e32 v0, 0x1048, v69
	ds_write2_b32 v0, v20, v21 offset1:1
	v_add_u32_e32 v0, 0x1450, v69
	ds_write2_b32 v0, v22, v23 offset1:1
	v_add_u32_e32 v0, 0x1458, v69
	ds_write2_b32 v0, v24, v25 offset1:1
	v_add_u32_e32 v0, 0x1860, v69
	ds_write2_b32 v0, v26, v27 offset1:1
	v_add_u32_e32 v0, 0x1868, v69
	ds_write2_b32 v0, v28, v29 offset1:1
	v_add_u32_e32 v0, 0x1c70, v69
	ds_write2_b32 v0, v30, v31 offset1:1
	v_add_u32_e32 v0, 0x1c78, v69
	ds_write2_b32 v0, v32, v33 offset1:1
	v_add_u32_e32 v0, 0x2080, v69
	ds_write2_b32 v0, v34, v35 offset1:1
	v_add_u32_e32 v0, 0x2088, v69
	ds_write2_b32 v0, v36, v37 offset1:1
	v_add_u32_e32 v0, 0x2490, v69
	ds_write2_b32 v0, v38, v39 offset1:1
	v_add_u32_e32 v0, 0x2498, v69
	ds_write2_b32 v0, v40, v41 offset1:1
	v_add_u32_e32 v0, 0x28a0, v69
	ds_write2_b32 v0, v42, v43 offset1:1
	v_add_u32_e32 v0, 0x28a8, v69
	ds_write2_b32 v0, v44, v45 offset1:1
	v_add_u32_e32 v0, 0x2cb0, v69
	ds_write2_b32 v0, v46, v47 offset1:1
	v_add_u32_e32 v0, 0x2cb8, v69
	ds_write2_b32 v0, v48, v49 offset1:1
	v_add_u32_e32 v0, 0x30c0, v69
	ds_write2_b32 v0, v50, v51 offset1:1
	v_add_u32_e32 v0, 0x30c8, v69
	ds_write2_b32 v0, v52, v53 offset1:1
	v_add_u32_e32 v0, 0x34d0, v69
	ds_write2_b32 v0, v54, v55 offset1:1
	v_add_u32_e32 v0, 0x34d8, v69
	ds_write2_b32 v0, v56, v57 offset1:1
	v_add_u32_e32 v0, 0x38e0, v69
	ds_write2_b32 v0, v58, v59 offset1:1
	v_add_u32_e32 v0, 0x38e8, v69
	ds_write2_b32 v0, v60, v61 offset1:1
	v_add_u32_e32 v0, 0x3cf0, v69
	ds_write2_b32 v0, v62, v63 offset1:1
	v_add_u32_e32 v0, 0x3cf8, v69
	ds_write2_b32 v0, v64, v65 offset1:1
	s_waitcnt lgkmcnt(0)
	v_add_u32_e32 v26, 0x400, v87
	ds_read2_b32 v[8:9], v87 offset0:65 offset1:73
	ds_read2_b32 v[10:11], v87 offset1:8
	ds_read2_b32 v[12:13], v87 offset0:130 offset1:138
	ds_read2_b32 v[14:15], v87 offset0:195 offset1:203
	ds_read2_b32 v[16:17], v26 offset0:4 offset1:12
	ds_read2_b32 v[18:19], v26 offset0:69 offset1:77
	ds_read2_b32 v[20:21], v26 offset0:134 offset1:142
	ds_read2_b32 v[22:23], v26 offset0:199 offset1:207
	v_or_b32_e32 v0, s10, v86
	v_lshlrev_b64 v[24:25], 9, v[0:1]
	s_waitcnt lgkmcnt(6)
	v_cvt_pk_bf16_f32 v4, v10, v8
	s_waitcnt lgkmcnt(4)
	v_cvt_pk_bf16_f32 v5, v12, v14
	s_waitcnt lgkmcnt(2)
	v_cvt_pk_bf16_f32 v6, v16, v18
	s_waitcnt lgkmcnt(0)
	v_cvt_pk_bf16_f32 v7, v20, v22
	v_lshl_add_u64 v[24:25], v[2:3], 0, v[24:25]
	v_or_b32_e32 v0, s10, v88
	global_store_dwordx4 v[24:25], v[4:7], off sc1
	s_nop 1
	v_cvt_pk_bf16_f32 v4, v11, v9
	v_lshlrev_b64 v[8:9], 9, v[0:1]
	v_cvt_pk_bf16_f32 v5, v13, v15
	v_cvt_pk_bf16_f32 v6, v17, v19
	v_cvt_pk_bf16_f32 v7, v21, v23
	v_lshl_add_u64 v[8:9], v[2:3], 0, v[8:9]
	global_store_dwordx4 v[8:9], v[4:7], off sc1
	ds_read2_b32 v[8:9], v87 offset0:81 offset1:89
	ds_read2_b32 v[10:11], v87 offset0:16 offset1:24
	ds_read2_b32 v[12:13], v87 offset0:146 offset1:154
	ds_read2_b32 v[14:15], v87 offset0:211 offset1:219
	ds_read2_b32 v[16:17], v26 offset0:20 offset1:28
	ds_read2_b32 v[18:19], v26 offset0:85 offset1:93
	ds_read2_b32 v[20:21], v26 offset0:150 offset1:158
	ds_read2_b32 v[22:23], v26 offset0:215 offset1:223
	v_or_b32_e32 v0, s10, v89
	v_lshlrev_b64 v[24:25], 9, v[0:1]
	s_waitcnt lgkmcnt(6)
	v_cvt_pk_bf16_f32 v4, v10, v8
	s_waitcnt lgkmcnt(4)
	v_cvt_pk_bf16_f32 v5, v12, v14
	s_waitcnt lgkmcnt(2)
	v_cvt_pk_bf16_f32 v6, v16, v18
	s_waitcnt lgkmcnt(0)
	v_cvt_pk_bf16_f32 v7, v20, v22
	v_lshl_add_u64 v[24:25], v[2:3], 0, v[24:25]
	v_or_b32_e32 v0, s10, v90
	global_store_dwordx4 v[24:25], v[4:7], off sc1
	s_nop 1
	v_cvt_pk_bf16_f32 v4, v11, v9
	v_lshlrev_b64 v[8:9], 9, v[0:1]
	v_cvt_pk_bf16_f32 v5, v13, v15
	v_cvt_pk_bf16_f32 v6, v17, v19
	v_cvt_pk_bf16_f32 v7, v21, v23
	v_lshl_add_u64 v[8:9], v[2:3], 0, v[8:9]
	global_store_dwordx4 v[8:9], v[4:7], off sc1
	ds_read2_b32 v[8:9], v87 offset0:32 offset1:40
	ds_read2_b32 v[10:11], v87 offset0:97 offset1:105
	ds_read2_b32 v[12:13], v87 offset0:162 offset1:170
	ds_read2_b32 v[14:15], v87 offset0:227 offset1:235
	ds_read2_b32 v[16:17], v26 offset0:36 offset1:44
	ds_read2_b32 v[18:19], v26 offset0:101 offset1:109
	ds_read2_b32 v[20:21], v26 offset0:166 offset1:174
	ds_read2_b32 v[22:23], v26 offset0:231 offset1:239
	v_or_b32_e32 v0, s10, v91
	v_lshlrev_b64 v[24:25], 9, v[0:1]
	s_waitcnt lgkmcnt(6)
	v_cvt_pk_bf16_f32 v4, v8, v10
	s_waitcnt lgkmcnt(4)
	v_cvt_pk_bf16_f32 v5, v12, v14
	s_waitcnt lgkmcnt(2)
	v_cvt_pk_bf16_f32 v6, v16, v18
	s_waitcnt lgkmcnt(0)
	v_cvt_pk_bf16_f32 v7, v20, v22
	v_lshl_add_u64 v[24:25], v[2:3], 0, v[24:25]
	v_or_b32_e32 v0, s10, v92
	global_store_dwordx4 v[24:25], v[4:7], off sc1
	s_nop 1
	v_cvt_pk_bf16_f32 v4, v9, v11
	v_lshlrev_b64 v[8:9], 9, v[0:1]
	v_cvt_pk_bf16_f32 v5, v13, v15
	v_cvt_pk_bf16_f32 v6, v17, v19
	v_cvt_pk_bf16_f32 v7, v21, v23
	v_lshl_add_u64 v[8:9], v[2:3], 0, v[8:9]
	global_store_dwordx4 v[8:9], v[4:7], off sc1
	ds_read2_b32 v[8:9], v87 offset0:48 offset1:56
	ds_read2_b32 v[10:11], v87 offset0:113 offset1:121
	ds_read2_b32 v[12:13], v87 offset0:178 offset1:186
	ds_read2_b32 v[14:15], v87 offset0:243 offset1:251
	ds_read2_b32 v[16:17], v26 offset0:52 offset1:60
	ds_read2_b32 v[18:19], v26 offset0:117 offset1:125
	ds_read2_b32 v[20:21], v26 offset0:182 offset1:190
	ds_read2_b32 v[22:23], v26 offset0:247 offset1:255
	v_or_b32_e32 v0, s10, v93
	v_lshlrev_b64 v[24:25], 9, v[0:1]
	s_waitcnt lgkmcnt(6)
	v_cvt_pk_bf16_f32 v4, v8, v10
	s_waitcnt lgkmcnt(4)
	v_cvt_pk_bf16_f32 v5, v12, v14
	s_waitcnt lgkmcnt(2)
	v_cvt_pk_bf16_f32 v6, v16, v18
	s_waitcnt lgkmcnt(0)
	v_cvt_pk_bf16_f32 v7, v20, v22
	v_lshl_add_u64 v[24:25], v[2:3], 0, v[24:25]
	v_or_b32_e32 v0, s10, v94
	global_store_dwordx4 v[24:25], v[4:7], off sc1
	s_nop 1
	v_cvt_pk_bf16_f32 v4, v9, v11
	v_lshlrev_b64 v[8:9], 9, v[0:1]
	v_cvt_pk_bf16_f32 v5, v13, v15
	v_cvt_pk_bf16_f32 v6, v17, v19
	v_cvt_pk_bf16_f32 v7, v21, v23
	v_lshl_add_u64 v[2:3], v[2:3], 0, v[8:9]
	global_store_dwordx4 v[2:3], v[4:7], off sc1
	s_waitcnt lgkmcnt(0)

.LBB0_872:
	s_andn2_b64 vcc, exec, s[10:11]
	s_cbranch_vccnz .LBB0_874
	s_and_b32 s0, s17, 0xfc0
	s_add_i32 s10, s0, 0xfffff400
	s_and_b32 s12, s7, 0x3c0
	v_or_b32_e32 v0, s10, v66
	s_lshl_b32 s0, s12, 2
	v_or_b32_e32 v4, 4, v0
	v_mov_b32_e32 v5, v1
	v_lshl_add_u64 v[62:63], v[78:79], 0, s[0:1]
	v_lshlrev_b64 v[2:3], 12, v[0:1]
	v_lshlrev_b64 v[4:5], 12, v[4:5]
	v_lshl_add_u64 v[2:3], v[62:63], 0, v[2:3]
	v_lshl_add_u64 v[6:7], v[62:63], 0, v[4:5]
	global_load_dwordx4 v[2:5], v[2:3], off
	s_nop 0
	global_load_dwordx4 v[6:9], v[6:7], off
	v_or_b32_e32 v10, 8, v0
	v_mov_b32_e32 v11, v1
	v_or_b32_e32 v12, 12, v0
	v_mov_b32_e32 v13, v1
	v_lshlrev_b64 v[10:11], 12, v[10:11]
	v_lshlrev_b64 v[12:13], 12, v[12:13]
	v_lshl_add_u64 v[10:11], v[62:63], 0, v[10:11]
	v_lshl_add_u64 v[14:15], v[62:63], 0, v[12:13]
	global_load_dwordx4 v[10:13], v[10:11], off
	s_nop 0
	global_load_dwordx4 v[14:17], v[14:15], off
	v_or_b32_e32 v18, 16, v0
	v_mov_b32_e32 v19, v1
	v_or_b32_e32 v20, 20, v0
	v_mov_b32_e32 v21, v1
	v_lshlrev_b64 v[18:19], 12, v[18:19]
	v_lshlrev_b64 v[20:21], 12, v[20:21]
	v_lshl_add_u64 v[18:19], v[62:63], 0, v[18:19]
	v_lshl_add_u64 v[22:23], v[62:63], 0, v[20:21]
	global_load_dwordx4 v[18:21], v[18:19], off
	s_nop 0
	global_load_dwordx4 v[22:25], v[22:23], off
	v_or_b32_e32 v26, 24, v0
	v_mov_b32_e32 v27, v1
	v_or_b32_e32 v28, 28, v0
	v_mov_b32_e32 v29, v1
	v_lshlrev_b64 v[26:27], 12, v[26:27]
	v_lshlrev_b64 v[28:29], 12, v[28:29]
	v_lshl_add_u64 v[26:27], v[62:63], 0, v[26:27]
	v_lshl_add_u64 v[30:31], v[62:63], 0, v[28:29]
	global_load_dwordx4 v[26:29], v[26:27], off
	s_nop 0
	global_load_dwordx4 v[30:33], v[30:31], off
	v_or_b32_e32 v34, 32, v0
	v_mov_b32_e32 v35, v1
	v_or_b32_e32 v36, 36, v0
	v_mov_b32_e32 v37, v1
	v_lshlrev_b64 v[34:35], 12, v[34:35]
	v_lshlrev_b64 v[36:37], 12, v[36:37]
	v_lshl_add_u64 v[34:35], v[62:63], 0, v[34:35]
	v_lshl_add_u64 v[38:39], v[62:63], 0, v[36:37]
	global_load_dwordx4 v[34:37], v[34:35], off
	s_nop 0
	global_load_dwordx4 v[38:41], v[38:39], off
	v_or_b32_e32 v42, 40, v0
	v_mov_b32_e32 v43, v1
	v_or_b32_e32 v44, 44, v0
	v_mov_b32_e32 v45, v1
	v_lshlrev_b64 v[42:43], 12, v[42:43]
	v_lshlrev_b64 v[44:45], 12, v[44:45]
	v_lshl_add_u64 v[42:43], v[62:63], 0, v[42:43]
	v_lshl_add_u64 v[46:47], v[62:63], 0, v[44:45]
	global_load_dwordx4 v[42:45], v[42:43], off
	s_nop 0
	global_load_dwordx4 v[46:49], v[46:47], off
	v_or_b32_e32 v50, 48, v0
	v_mov_b32_e32 v51, v1
	v_lshlrev_b64 v[50:51], 12, v[50:51]
	v_lshl_add_u64 v[50:51], v[62:63], 0, v[50:51]
	v_or_b32_e32 v54, 52, v0
	v_mov_b32_e32 v55, v1
	global_load_dwordx4 v[50:53], v[50:51], off
	v_lshlrev_b64 v[54:55], 12, v[54:55]
	v_lshl_add_u64 v[54:55], v[62:63], 0, v[54:55]
	v_or_b32_e32 v58, 56, v0
	v_mov_b32_e32 v59, v1
	global_load_dwordx4 v[54:57], v[54:55], off
	v_lshlrev_b64 v[58:59], 12, v[58:59]
	v_lshl_add_u64 v[58:59], v[62:63], 0, v[58:59]
	v_or_b32_e32 v0, 60, v0
	global_load_dwordx4 v[58:61], v[58:59], off
	v_lshlrev_b64 v[64:65], 12, v[0:1]
	v_lshl_add_u64 v[62:63], v[62:63], 0, v[64:65]
	global_load_dwordx4 v[62:65], v[62:63], off
	v_add_u32_e32 v0, 0x410, v69
	s_mov_b32 s11, s1
	s_waitcnt vmcnt(0)
	ds_write2_b32 v69, v2, v3 offset1:1
	ds_write2_b32 v69, v4, v5 offset0:2 offset1:3
	ds_write2_b32 v0, v6, v7 offset1:1
	v_add_u32_e32 v0, 0x418, v69
	ds_write2_b32 v0, v8, v9 offset1:1
	v_add_u32_e32 v0, 0x820, v69
	ds_write2_b32 v0, v10, v11 offset1:1
	v_add_u32_e32 v0, 0x828, v69
	ds_write2_b32 v0, v12, v13 offset1:1
	v_add_u32_e32 v0, 0xc30, v69
	ds_write2_b32 v0, v14, v15 offset1:1
	v_add_u32_e32 v0, 0xc38, v69
	ds_write2_b32 v0, v16, v17 offset1:1
	v_add_u32_e32 v0, 0x1040, v69
	ds_write2_b32 v0, v18, v19 offset1:1
	v_add_u32_e32 v0, 0x1048, v69
	ds_write2_b32 v0, v20, v21 offset1:1
	v_add_u32_e32 v0, 0x1450, v69
	ds_write2_b32 v0, v22, v23 offset1:1
	v_add_u32_e32 v0, 0x1458, v69
	ds_write2_b32 v0, v24, v25 offset1:1
	v_add_u32_e32 v0, 0x1860, v69
	v_lshl_add_u64 v[22:23], s[10:11], 1, v[74:75]
	ds_write2_b32 v0, v26, v27 offset1:1
	v_add_u32_e32 v0, 0x1868, v69
	ds_write2_b32 v0, v28, v29 offset1:1
	v_add_u32_e32 v0, 0x1c70, v69
	ds_write2_b32 v0, v30, v31 offset1:1
	v_add_u32_e32 v0, 0x1c78, v69
	ds_write2_b32 v0, v32, v33 offset1:1
	v_add_u32_e32 v0, 0x2080, v69
	v_add_u32_e32 v26, 0x400, v87
	ds_write2_b32 v0, v34, v35 offset1:1
	v_add_u32_e32 v0, 0x2088, v69
	ds_write2_b32 v0, v36, v37 offset1:1
	v_add_u32_e32 v0, 0x2490, v69
	ds_write2_b32 v0, v38, v39 offset1:1
	v_add_u32_e32 v0, 0x2498, v69
	ds_write2_b32 v0, v40, v41 offset1:1
	v_add_u32_e32 v0, 0x28a0, v69
	ds_write2_b32 v0, v42, v43 offset1:1
	v_add_u32_e32 v0, 0x28a8, v69
	ds_write2_b32 v0, v44, v45 offset1:1
	v_add_u32_e32 v0, 0x2cb0, v69
	ds_write2_b32 v0, v46, v47 offset1:1
	v_add_u32_e32 v0, 0x2cb8, v69
	ds_write2_b32 v0, v48, v49 offset1:1
	v_add_u32_e32 v0, 0x30c0, v69
	ds_write2_b32 v0, v50, v51 offset1:1
	v_add_u32_e32 v0, 0x30c8, v69
	ds_write2_b32 v0, v52, v53 offset1:1
	v_add_u32_e32 v0, 0x34d0, v69
	ds_write2_b32 v0, v54, v55 offset1:1
	v_add_u32_e32 v0, 0x34d8, v69
	ds_write2_b32 v0, v56, v57 offset1:1
	v_add_u32_e32 v0, 0x38e0, v69
	ds_write2_b32 v0, v58, v59 offset1:1
	v_add_u32_e32 v0, 0x38e8, v69
	ds_write2_b32 v0, v60, v61 offset1:1
	v_add_u32_e32 v0, 0x3cf0, v69
	ds_write2_b32 v0, v62, v63 offset1:1
	v_add_u32_e32 v0, 0x3cf8, v69
	ds_write2_b32 v0, v64, v65 offset1:1
	s_waitcnt lgkmcnt(0)
	ds_read2_b32 v[6:7], v87 offset0:65 offset1:73
	ds_read2_b32 v[8:9], v87 offset1:8
	ds_read2_b32 v[10:11], v87 offset0:130 offset1:138
	ds_read2_b32 v[12:13], v87 offset0:195 offset1:203
	ds_read2_b32 v[14:15], v26 offset0:4 offset1:12
	ds_read2_b32 v[16:17], v26 offset0:69 offset1:77
	ds_read2_b32 v[18:19], v26 offset0:134 offset1:142
	ds_read2_b32 v[20:21], v26 offset0:199 offset1:207
	v_or_b32_e32 v0, s12, v86
	v_lshlrev_b32_e32 v0, 11, v0
	s_waitcnt lgkmcnt(6)
	v_cvt_pk_bf16_f32 v2, v8, v6
	s_waitcnt lgkmcnt(4)
	v_cvt_pk_bf16_f32 v3, v10, v12
	s_waitcnt lgkmcnt(2)
	v_cvt_pk_bf16_f32 v4, v14, v16
	s_waitcnt lgkmcnt(0)
	v_cvt_pk_bf16_f32 v5, v18, v20
	v_lshl_add_u64 v[24:25], v[22:23], 0, v[0:1]
	global_store_dwordx4 v[24:25], v[2:5], off sc1
	v_or_b32_e32 v0, s12, v88
	v_lshlrev_b32_e32 v0, 11, v0
	v_cvt_pk_bf16_f32 v2, v9, v7
	v_cvt_pk_bf16_f32 v3, v11, v13
	v_cvt_pk_bf16_f32 v4, v15, v17
	v_cvt_pk_bf16_f32 v5, v19, v21
	ds_read2_b32 v[8:9], v87 offset0:81 offset1:89
	ds_read2_b32 v[10:11], v87 offset0:16 offset1:24
	ds_read2_b32 v[12:13], v87 offset0:146 offset1:154
	ds_read2_b32 v[14:15], v87 offset0:211 offset1:219
	ds_read2_b32 v[16:17], v26 offset0:20 offset1:28
	ds_read2_b32 v[18:19], v26 offset0:85 offset1:93
	ds_read2_b32 v[20:21], v26 offset0:150 offset1:158
	ds_read2_b32 v[24:25], v26 offset0:215 offset1:223
	v_lshl_add_u64 v[6:7], v[22:23], 0, v[0:1]
	v_or_b32_e32 v0, s12, v89
	v_lshlrev_b32_e32 v0, 11, v0
	global_store_dwordx4 v[6:7], v[2:5], off sc1
	v_lshl_add_u64 v[6:7], v[22:23], 0, v[0:1]
	v_or_b32_e32 v0, s12, v90
	s_waitcnt lgkmcnt(6)
	v_cvt_pk_bf16_f32 v2, v10, v8
	s_waitcnt lgkmcnt(4)
	v_cvt_pk_bf16_f32 v3, v12, v14
	s_waitcnt lgkmcnt(2)
	v_cvt_pk_bf16_f32 v4, v16, v18
	s_waitcnt lgkmcnt(0)
	v_cvt_pk_bf16_f32 v5, v20, v24
	global_store_dwordx4 v[6:7], v[2:5], off sc1
	v_lshlrev_b32_e32 v0, 11, v0
	v_lshl_add_u64 v[6:7], v[22:23], 0, v[0:1]
	v_cvt_pk_bf16_f32 v2, v11, v9
	v_cvt_pk_bf16_f32 v3, v13, v15
	v_cvt_pk_bf16_f32 v4, v17, v19
	v_cvt_pk_bf16_f32 v5, v21, v25
	ds_read2_b32 v[8:9], v87 offset0:32 offset1:40
	ds_read2_b32 v[10:11], v87 offset0:97 offset1:105
	ds_read2_b32 v[12:13], v87 offset0:162 offset1:170
	ds_read2_b32 v[14:15], v87 offset0:227 offset1:235
	ds_read2_b32 v[16:17], v26 offset0:36 offset1:44
	ds_read2_b32 v[18:19], v26 offset0:101 offset1:109
	ds_read2_b32 v[20:21], v26 offset0:166 offset1:174
	ds_read2_b32 v[24:25], v26 offset0:231 offset1:239
	v_or_b32_e32 v0, s12, v91
	v_lshlrev_b32_e32 v0, 11, v0
	global_store_dwordx4 v[6:7], v[2:5], off sc1
	v_lshl_add_u64 v[6:7], v[22:23], 0, v[0:1]
	v_or_b32_e32 v0, s12, v92
	s_waitcnt lgkmcnt(6)
	v_cvt_pk_bf16_f32 v2, v8, v10
	s_waitcnt lgkmcnt(4)
	v_cvt_pk_bf16_f32 v3, v12, v14
	s_waitcnt lgkmcnt(2)
	v_cvt_pk_bf16_f32 v4, v16, v18
	s_waitcnt lgkmcnt(0)
	v_cvt_pk_bf16_f32 v5, v20, v24
	global_store_dwordx4 v[6:7], v[2:5], off sc1
	v_lshlrev_b32_e32 v0, 11, v0
	v_lshl_add_u64 v[6:7], v[22:23], 0, v[0:1]
	v_cvt_pk_bf16_f32 v2, v9, v11
	v_cvt_pk_bf16_f32 v3, v13, v15
	v_cvt_pk_bf16_f32 v4, v17, v19
	v_cvt_pk_bf16_f32 v5, v21, v25
	ds_read2_b32 v[8:9], v87 offset0:48 offset1:56
	ds_read2_b32 v[10:11], v87 offset0:113 offset1:121
	ds_read2_b32 v[12:13], v87 offset0:178 offset1:186
	ds_read2_b32 v[14:15], v87 offset0:243 offset1:251
	ds_read2_b32 v[16:17], v26 offset0:52 offset1:60
	ds_read2_b32 v[18:19], v26 offset0:117 offset1:125
	ds_read2_b32 v[20:21], v26 offset0:182 offset1:190
	ds_read2_b32 v[24:25], v26 offset0:247 offset1:255
	v_or_b32_e32 v0, s12, v93
	v_lshlrev_b32_e32 v0, 11, v0
	global_store_dwordx4 v[6:7], v[2:5], off sc1
	v_lshl_add_u64 v[6:7], v[22:23], 0, v[0:1]
	v_or_b32_e32 v0, s12, v94
	s_waitcnt lgkmcnt(6)
	v_cvt_pk_bf16_f32 v2, v8, v10
	s_waitcnt lgkmcnt(4)
	v_cvt_pk_bf16_f32 v3, v12, v14
	s_waitcnt lgkmcnt(2)
	v_cvt_pk_bf16_f32 v4, v16, v18
	s_waitcnt lgkmcnt(0)
	v_cvt_pk_bf16_f32 v5, v20, v24
	v_lshlrev_b32_e32 v0, 11, v0
	global_store_dwordx4 v[6:7], v[2:5], off sc1
	v_lshl_add_u64 v[6:7], v[22:23], 0, v[0:1]
	s_nop 0
	v_cvt_pk_bf16_f32 v2, v9, v11
	v_cvt_pk_bf16_f32 v3, v13, v15
	v_cvt_pk_bf16_f32 v4, v17, v19
	v_cvt_pk_bf16_f32 v5, v21, v25
	global_store_dwordx4 v[6:7], v[2:5], off sc1
	s_waitcnt lgkmcnt(0)
